# v022
# baseline (speedup 1.0000x reference)
.LBB0_321:
	v_exp_f32_e32 v212, v96
	v_exp_f32_e32 v213, v97
	v_exp_f32_e32 v214, v98
	v_exp_f32_e32 v215, v99
	v_exp_f32_e32 v216, v100
	v_exp_f32_e32 v217, v101
	v_exp_f32_e32 v218, v102
	v_exp_f32_e32 v219, v103
	v_cvt_pk_bf16_f32 v96, v212, v213
	v_cvt_pk_bf16_f32 v97, v214, v215
	v_cvt_pk_bf16_f32 v98, v216, v217
	v_cvt_pk_bf16_f32 v99, v218, v219
	s_waitcnt lgkmcnt(4)
	s_nop 0
	v_mfma_f32_32x32x16_bf16 v[48:63], v[6:9], v[96:99], v[48:63]
	s_waitcnt lgkmcnt(2)
	v_mfma_f32_32x32x16_bf16 v[32:47], v[10:13], v[96:99], v[32:47]
	ds_read_b64_tr_b16 v[6:7], v14 offset:20480
	ds_read_b64_tr_b16 v[8:9], v15 offset:20480
	ds_read_b64_tr_b16 v[10:11], v202 offset:20480
	ds_read_b64_tr_b16 v[12:13], v203 offset:20480
	ds_read_b64_tr_b16 v[100:101], v204 offset:20480
	ds_read_b64_tr_b16 v[102:103], v205 offset:20480
	ds_read_b64_tr_b16 v[112:113], v206 offset:20480
	ds_read_b64_tr_b16 v[114:115], v207 offset:20480
	v_mfma_f32_32x32x16_bf16 v[64:79], v[160:163], v[96:99], v[64:79]
	s_waitcnt lgkmcnt(8)
	v_mfma_f32_32x32x16_bf16 v[16:31], v[2:5], v[96:99], v[16:31]
	v_add_f32_e32 v201, v212, v201
	v_add_f32_e32 v201, v213, v201
	v_add_f32_e32 v201, v214, v201
	v_add_f32_e32 v201, v215, v201
	v_add_f32_e32 v201, v216, v201
	v_add_f32_e32 v201, v217, v201
	v_add_f32_e32 v201, v218, v201
	v_add_f32_e32 v201, v219, v201
	v_exp_f32_e32 v220, v104
	v_exp_f32_e32 v221, v105
	v_exp_f32_e32 v222, v106
	v_exp_f32_e32 v223, v107
	v_exp_f32_e32 v224, v108
	v_exp_f32_e32 v225, v109
	v_exp_f32_e32 v228, v110
	v_exp_f32_e32 v246, v111
	v_cvt_pk_bf16_f32 v2, v220, v221
	v_cvt_pk_bf16_f32 v3, v222, v223
	v_cvt_pk_bf16_f32 v4, v224, v225
	v_cvt_pk_bf16_f32 v5, v228, v246
	s_waitcnt lgkmcnt(6)
	s_nop 0
	v_mfma_f32_32x32x16_bf16 v[64:79], v[6:9], v[2:5], v[64:79]
	s_waitcnt lgkmcnt(4)
	v_mfma_f32_32x32x16_bf16 v[48:63], v[10:13], v[2:5], v[48:63]
	s_waitcnt lgkmcnt(2)
	v_mfma_f32_32x32x16_bf16 v[32:47], v[100:103], v[2:5], v[32:47]
	ds_read_b64_tr_b16 v[6:7], v14 offset:24576
	ds_read_b64_tr_b16 v[8:9], v15 offset:24576
	ds_read_b64_tr_b16 v[10:11], v202 offset:24576
	ds_read_b64_tr_b16 v[12:13], v203 offset:24576
	ds_read_b64_tr_b16 v[96:97], v204 offset:24576
	ds_read_b64_tr_b16 v[98:99], v205 offset:24576
	ds_read_b64_tr_b16 v[100:101], v206 offset:24576
	ds_read_b64_tr_b16 v[102:103], v207 offset:24576
	s_waitcnt lgkmcnt(8)
	v_mfma_f32_32x32x16_bf16 v[16:31], v[112:115], v[2:5], v[16:31]
	v_add_f32_e32 v201, v220, v201
	v_add_f32_e32 v201, v221, v201
	v_add_f32_e32 v201, v222, v201
	v_add_f32_e32 v201, v223, v201
	v_add_f32_e32 v201, v224, v201
	v_add_f32_e32 v201, v225, v201
	v_add_f32_e32 v201, v228, v201
	v_add_f32_e32 v201, v246, v201
	v_exp_f32_e32 v247, v80
	v_exp_f32_e32 v248, v81
	v_exp_f32_e32 v249, v82
	v_exp_f32_e32 v250, v83
	v_exp_f32_e32 v251, v84
	v_exp_f32_e32 v252, v85
	v_exp_f32_e32 v231, v86
	v_exp_f32_e32 v232, v87
	v_cvt_pk_bf16_f32 v2, v247, v248
	v_cvt_pk_bf16_f32 v3, v249, v250
	v_cvt_pk_bf16_f32 v4, v251, v252
	v_cvt_pk_bf16_f32 v5, v231, v232
	s_waitcnt lgkmcnt(6)
	s_nop 0
	v_mfma_f32_32x32x16_bf16 v[64:79], v[6:9], v[2:5], v[64:79]
	s_waitcnt lgkmcnt(4)
	v_mfma_f32_32x32x16_bf16 v[48:63], v[10:13], v[2:5], v[48:63]
	ds_read_b64_tr_b16 v[6:7], v14 offset:28672
	ds_read_b64_tr_b16 v[8:9], v15 offset:28672
	ds_read_b64_tr_b16 v[10:11], v202 offset:28672
	ds_read_b64_tr_b16 v[12:13], v203 offset:28672
	ds_read_b64_tr_b16 v[80:81], v204 offset:28672
	ds_read_b64_tr_b16 v[82:83], v205 offset:28672
	ds_read_b64_tr_b16 v[84:85], v206 offset:28672
	ds_read_b64_tr_b16 v[86:87], v207 offset:28672
	s_waitcnt lgkmcnt(10)
	v_mfma_f32_32x32x16_bf16 v[32:47], v[96:99], v[2:5], v[32:47]
	s_waitcnt lgkmcnt(8)
	v_mfma_f32_32x32x16_bf16 v[16:31], v[100:103], v[2:5], v[16:31]
	v_add_f32_e32 v201, v247, v201
	v_add_f32_e32 v201, v248, v201
	v_add_f32_e32 v201, v249, v201
	v_add_f32_e32 v201, v250, v201
	v_add_f32_e32 v201, v251, v201
	v_add_f32_e32 v201, v252, v201
	v_add_f32_e32 v201, v231, v201
	v_add_f32_e32 v201, v232, v201
	v_exp_f32_e32 v233, v88
	v_exp_f32_e32 v234, v89
	v_exp_f32_e32 v235, v90
	v_exp_f32_e32 v236, v91
	v_exp_f32_e32 v237, v92
	v_exp_f32_e32 v238, v93
	v_exp_f32_e32 v239, v94
	v_exp_f32_e32 v240, v95
	v_cvt_pk_bf16_f32 v2, v233, v234
	v_cvt_pk_bf16_f32 v3, v235, v236
	v_cvt_pk_bf16_f32 v4, v237, v238
	v_cvt_pk_bf16_f32 v5, v239, v240
	s_waitcnt lgkmcnt(6)
	s_nop 0
	v_mfma_f32_32x32x16_bf16 v[64:79], v[6:9], v[2:5], v[64:79]
	s_waitcnt lgkmcnt(4)
	v_mfma_f32_32x32x16_bf16 v[48:63], v[10:13], v[2:5], v[48:63]
	s_waitcnt lgkmcnt(2)
	v_mfma_f32_32x32x16_bf16 v[32:47], v[80:83], v[2:5], v[32:47]
	s_waitcnt lgkmcnt(0)
	v_mfma_f32_32x32x16_bf16 v[16:31], v[84:87], v[2:5], v[16:31]
	v_add_f32_e32 v201, v233, v201
	v_add_f32_e32 v201, v234, v201
	v_add_f32_e32 v201, v235, v201
	v_add_f32_e32 v201, v236, v201
	v_add_f32_e32 v201, v237, v201
	v_add_f32_e32 v201, v238, v201
	v_add_f32_e32 v201, v239, v201
	v_add_f32_e32 v201, v240, v201
	ds_read_b128 v[2:5], v210 offset:32768
	ds_read_b128 v[6:9], v210 offset:40960
	s_or_b32 s18, s80, 64
	v_add_u32_e32 v0, s18, v198
	s_or_b32 s14, s80, 0x7f
	s_waitcnt lgkmcnt(1)
	v_mfma_f32_32x32x16_bf16 v[112:127], v[2:5], v[144:147], 0
	ds_read_b128 v[2:5], v208 offset:32768
	ds_read_b128 v[10:13], v208 offset:40960
	ds_read_b128 v[80:83], v209 offset:32768
	v_cvt_f32_i32_e32 v0, v0
	s_cmp_ge_i32 s14, s23
	s_cselect_b64 s[14:15], -1, 0
	s_cmp_le_i32 s18, s47
	s_cselect_b64 s[16:17], -1, 0
	s_waitcnt lgkmcnt(2)
	v_mfma_f32_32x32x16_bf16 v[112:127], v[2:5], v[148:151], v[112:127]
	ds_read_b128 v[2:5], v209 offset:40960
	ds_read_b128 v[84:87], v211 offset:32768
	ds_read_b128 v[88:91], v211 offset:40960
	s_waitcnt lgkmcnt(3)
	v_mfma_f32_32x32x16_bf16 v[112:127], v[80:83], v[152:155], v[112:127]
	v_mfma_f32_32x32x16_bf16 v[128:143], v[6:9], v[144:147], 0
	v_mfma_f32_32x32x16_bf16 v[128:143], v[10:13], v[148:151], v[128:143]
	s_waitcnt lgkmcnt(2)
	v_mfma_f32_32x32x16_bf16 v[128:143], v[2:5], v[152:155], v[128:143]
	ds_read_b64_tr_b16 v[160:161], v14 offset:49152
	ds_read_b64_tr_b16 v[162:163], v15 offset:49152
	ds_read_b64_tr_b16 v[10:11], v202 offset:49152
	ds_read_b64_tr_b16 v[12:13], v203 offset:49152
	ds_read_b64_tr_b16 v[6:7], v204 offset:49152
	ds_read_b64_tr_b16 v[8:9], v205 offset:49152
	ds_read_b64_tr_b16 v[2:3], v206 offset:49152
	ds_read_b64_tr_b16 v[4:5], v207 offset:49152
	s_waitcnt lgkmcnt(8)
	v_mfma_f32_32x32x16_bf16 v[128:143], v[88:91], v[156:159], v[128:143]
	v_mfma_f32_32x32x16_bf16 v[112:127], v[84:87], v[156:159], v[112:127]
	s_and_b64 s[18:19], s[14:15], s[16:17]
	s_mov_b64 s[16:17], -1
	s_and_b64 vcc, exec, s[18:19]
	s_cbranch_vccnz .LBB0_323
	v_cndmask_b32_e64 v94, v176, -v176, s[14:15]
	v_fma_f32 v208, v94, v0, -v180
	v_fma_f32 v80, 0, v94, v208
	v_add_f32_e32 v81, v94, v208
	s_nop 3
	v_fma_f32 v96, v112, s62, v80
	v_fma_f32 v97, v113, s62, v81
	v_fma_f32 v80, v94, s76, v208
	v_fma_f32 v81, v94, s77, v208
	v_max3_f32 v82, v96, s36, v97
	v_fma_f32 v98, v114, s62, v80
	v_fma_f32 v99, v115, s62, v81
	v_fma_f32 v80, v94, s70, v208
	v_fma_f32 v81, v94, s71, v208
	v_max3_f32 v82, v82, v98, v99
	v_fma_f32 v100, v116, s62, v80
	v_fma_f32 v101, v117, s62, v81
	v_fma_f32 v80, v94, s74, v208
	v_fma_f32 v81, v94, s75, v208
	v_max3_f32 v82, v82, v100, v101
	v_fma_f32 v102, v118, s62, v80
	v_fma_f32 v103, v119, s62, v81
	v_fma_f32 v80, v94, s28, v208
	v_fma_f32 v81, v94, s29, v208
	v_max3_f32 v82, v82, v102, v103
	v_fma_f32 v104, v120, s62, v80
	v_fma_f32 v105, v121, s62, v81
	v_fma_f32 v80, v94, s26, v208
	v_fma_f32 v81, v94, s27, v208
	v_max3_f32 v82, v82, v104, v105
	v_fma_f32 v106, v122, s62, v80
	v_fma_f32 v107, v123, s62, v81
	v_fma_f32 v80, v94, s86, v208
	v_fma_f32 v81, v94, s87, v208
	v_max3_f32 v82, v82, v106, v107
	v_fma_f32 v108, v124, s62, v80
	v_fma_f32 v109, v125, s62, v81
	v_fma_f32 v80, v94, s72, v208
	v_fma_f32 v81, v94, s73, v208
	v_max3_f32 v82, v82, v108, v109
	v_fma_f32 v110, v126, s62, v80
	v_fma_f32 v111, v127, s62, v81
	s_nop 0
	v_max3_f32 v82, v82, v110, v111
	v_fma_f32 v80, v94, s68, v208
	v_fma_f32 v81, v94, s69, v208
	v_fma_f32 v80, v128, s62, v80
	v_fma_f32 v81, v129, s62, v81
	s_mov_b64 s[16:17], 0
	v_max3_f32 v84, v82, v80, v81
	v_fma_f32 v82, v94, s60, v208
	v_fma_f32 v83, v94, s61, v208
	v_fma_f32 v82, v130, s62, v82
	v_fma_f32 v83, v131, s62, v83
	s_nop 0
	v_max3_f32 v86, v84, v82, v83
	v_fma_f32 v84, v94, s34, v208
	v_fma_f32 v85, v94, s35, v208
	v_fma_f32 v84, v132, s62, v84
	v_fma_f32 v85, v133, s62, v85
	s_nop 0
	v_max3_f32 v88, v86, v84, v85
	v_fma_f32 v86, v94, s88, v208
	v_fma_f32 v87, v94, s89, v208
	v_fma_f32 v86, v134, s62, v86
	v_fma_f32 v87, v135, s62, v87
	s_nop 0
	v_max3_f32 v90, v88, v86, v87
	v_fma_f32 v88, v94, s90, v208
	v_fma_f32 v89, v94, s91, v208
	v_fma_f32 v88, v136, s62, v88
	v_fma_f32 v89, v137, s62, v89
	s_nop 0
	v_max3_f32 v92, v90, v88, v89
	v_fma_f32 v90, v94, s92, v208
	v_fma_f32 v91, v94, s93, v208
	v_fma_f32 v90, v138, s62, v90
	v_fma_f32 v91, v139, s62, v91
	s_nop 0
	v_max3_f32 v95, v92, v90, v91
	v_fma_f32 v92, v94, s94, v208
	v_fma_f32 v93, v94, s95, v208
	v_fma_f32 v92, v140, s62, v92
	v_fma_f32 v93, v141, s62, v93
	s_nop 0
	v_max3_f32 v209, v95, v92, v93
	v_fma_f32 v95, v94, s97, v208
	v_fma_f32 v94, v94, s96, v208
	v_fma_f32 v94, v142, s62, v94
	v_fma_f32 v95, v143, s62, v95
	s_nop 0
	v_max3_f32 v208, v209, v94, v95

.LBB0_325:
	v_mov_b32_e32 v112, v208
	v_mov_b32_e32 v0, v201
	s_nop 0
	v_permlane32_swap_b32_e32 v208, v112
	v_max_f32_e32 v112, v112, v112
	s_nop 0
	v_max_f32_e32 v113, v208, v208
	v_max_f32_e32 v112, v113, v112
	v_cmp_lt_f32_e32 vcc, s70, v112
	s_cbranch_vccz .LBB0_327
	v_max_f32_e32 v112, v112, v112
	v_max_f32_e32 v113, 0, v112
	v_exp_f32_e64 v112, -v113
	v_sub_f32_e32 v95, v95, v113
	v_sub_f32_e32 v94, v94, v113
	v_sub_f32_e32 v93, v93, v113
	v_sub_f32_e32 v92, v92, v113
	v_sub_f32_e32 v91, v91, v113
	v_sub_f32_e32 v90, v90, v113
	v_sub_f32_e32 v89, v89, v113
	v_sub_f32_e32 v88, v88, v113
	v_sub_f32_e32 v87, v87, v113
	v_sub_f32_e32 v86, v86, v113
	v_sub_f32_e32 v85, v85, v113
	v_sub_f32_e32 v84, v84, v113
	v_sub_f32_e32 v83, v83, v113
	v_sub_f32_e32 v82, v82, v113
	v_sub_f32_e32 v81, v81, v113
	v_sub_f32_e32 v80, v80, v113
	v_sub_f32_e32 v111, v111, v113
	v_sub_f32_e32 v110, v110, v113
	v_sub_f32_e32 v109, v109, v113
	v_sub_f32_e32 v108, v108, v113
	v_sub_f32_e32 v107, v107, v113
	v_sub_f32_e32 v106, v106, v113
	v_sub_f32_e32 v105, v105, v113
	v_sub_f32_e32 v104, v104, v113
	v_sub_f32_e32 v103, v103, v113
	v_sub_f32_e32 v102, v102, v113
	v_sub_f32_e32 v101, v101, v113
	v_sub_f32_e32 v100, v100, v113
	v_sub_f32_e32 v99, v99, v113
	v_sub_f32_e32 v98, v98, v113
	v_sub_f32_e32 v97, v97, v113
	v_sub_f32_e32 v96, v96, v113
	v_add_f32_e32 v180, v180, v113
	v_pk_mul_f32 v[78:79], v[78:79], v[112:113] op_sel_hi:[1,0]
	v_pk_mul_f32 v[76:77], v[76:77], v[112:113] op_sel_hi:[1,0]
	v_pk_mul_f32 v[74:75], v[74:75], v[112:113] op_sel_hi:[1,0]
	v_pk_mul_f32 v[72:73], v[72:73], v[112:113] op_sel_hi:[1,0]
	v_pk_mul_f32 v[70:71], v[70:71], v[112:113] op_sel_hi:[1,0]
	v_pk_mul_f32 v[68:69], v[68:69], v[112:113] op_sel_hi:[1,0]
	v_pk_mul_f32 v[66:67], v[66:67], v[112:113] op_sel_hi:[1,0]
	v_pk_mul_f32 v[64:65], v[64:65], v[112:113] op_sel_hi:[1,0]
	v_pk_mul_f32 v[62:63], v[62:63], v[112:113] op_sel_hi:[1,0]
	v_pk_mul_f32 v[60:61], v[60:61], v[112:113] op_sel_hi:[1,0]
	v_pk_mul_f32 v[58:59], v[58:59], v[112:113] op_sel_hi:[1,0]
	v_pk_mul_f32 v[56:57], v[56:57], v[112:113] op_sel_hi:[1,0]
	v_pk_mul_f32 v[54:55], v[54:55], v[112:113] op_sel_hi:[1,0]
	v_pk_mul_f32 v[52:53], v[52:53], v[112:113] op_sel_hi:[1,0]
	v_pk_mul_f32 v[50:51], v[50:51], v[112:113] op_sel_hi:[1,0]
	v_pk_mul_f32 v[48:49], v[48:49], v[112:113] op_sel_hi:[1,0]
	v_pk_mul_f32 v[46:47], v[46:47], v[112:113] op_sel_hi:[1,0]
	v_pk_mul_f32 v[44:45], v[44:45], v[112:113] op_sel_hi:[1,0]
	v_pk_mul_f32 v[42:43], v[42:43], v[112:113] op_sel_hi:[1,0]
	v_pk_mul_f32 v[40:41], v[40:41], v[112:113] op_sel_hi:[1,0]
	v_pk_mul_f32 v[38:39], v[38:39], v[112:113] op_sel_hi:[1,0]
	v_pk_mul_f32 v[36:37], v[36:37], v[112:113] op_sel_hi:[1,0]
	v_pk_mul_f32 v[34:35], v[34:35], v[112:113] op_sel_hi:[1,0]
	v_pk_mul_f32 v[32:33], v[32:33], v[112:113] op_sel_hi:[1,0]
	v_pk_mul_f32 v[30:31], v[30:31], v[112:113] op_sel_hi:[1,0]
	v_pk_mul_f32 v[28:29], v[28:29], v[112:113] op_sel_hi:[1,0]
	v_pk_mul_f32 v[26:27], v[26:27], v[112:113] op_sel_hi:[1,0]
	v_pk_mul_f32 v[24:25], v[24:25], v[112:113] op_sel_hi:[1,0]
	v_pk_mul_f32 v[22:23], v[22:23], v[112:113] op_sel_hi:[1,0]
	v_pk_mul_f32 v[20:21], v[20:21], v[112:113] op_sel_hi:[1,0]
	v_pk_mul_f32 v[18:19], v[18:19], v[112:113] op_sel_hi:[1,0]
	v_pk_mul_f32 v[16:17], v[16:17], v[112:113] op_sel_hi:[1,0]
	v_mul_f32_e32 v0, v0, v112
.LBB0_327:
	v_exp_f32_e32 v116, v96
	v_exp_f32_e32 v117, v97
	v_exp_f32_e32 v118, v98
	v_exp_f32_e32 v119, v99
	v_exp_f32_e32 v120, v100
	v_exp_f32_e32 v121, v101
	v_exp_f32_e32 v122, v102
	v_exp_f32_e32 v123, v103
	v_cvt_pk_bf16_f32 v96, v116, v117
	v_cvt_pk_bf16_f32 v97, v118, v119
	v_cvt_pk_bf16_f32 v98, v120, v121
	v_cvt_pk_bf16_f32 v99, v122, v123
	s_waitcnt lgkmcnt(4)
	s_nop 0
	v_mfma_f32_32x32x16_bf16 v[48:63], v[10:13], v[96:99], v[48:63]
	s_waitcnt lgkmcnt(2)
	v_mfma_f32_32x32x16_bf16 v[32:47], v[6:9], v[96:99], v[32:47]
	ds_read_b64_tr_b16 v[6:7], v14 offset:53248
	ds_read_b64_tr_b16 v[8:9], v15 offset:53248
	ds_read_b64_tr_b16 v[10:11], v202 offset:53248
	ds_read_b64_tr_b16 v[12:13], v203 offset:53248
	ds_read_b64_tr_b16 v[100:101], v204 offset:53248
	ds_read_b64_tr_b16 v[102:103], v205 offset:53248
	ds_read_b64_tr_b16 v[112:113], v206 offset:53248
	ds_read_b64_tr_b16 v[114:115], v207 offset:53248
	v_mfma_f32_32x32x16_bf16 v[64:79], v[160:163], v[96:99], v[64:79]
	s_waitcnt lgkmcnt(8)
	v_mfma_f32_32x32x16_bf16 v[16:31], v[2:5], v[96:99], v[16:31]
	v_add_f32_e32 v0, v116, v0
	v_add_f32_e32 v0, v117, v0
	v_add_f32_e32 v0, v118, v0
	v_add_f32_e32 v0, v119, v0
	v_add_f32_e32 v0, v120, v0
	v_add_f32_e32 v0, v121, v0
	v_add_f32_e32 v0, v122, v0
	v_add_f32_e32 v0, v123, v0
	v_exp_f32_e32 v104, v104
	v_exp_f32_e32 v105, v105
	v_exp_f32_e32 v106, v106
	v_exp_f32_e32 v107, v107
	v_exp_f32_e32 v108, v108
	v_exp_f32_e32 v109, v109
	v_exp_f32_e32 v110, v110
	v_exp_f32_e32 v111, v111
	v_cvt_pk_bf16_f32 v2, v104, v105
	v_cvt_pk_bf16_f32 v3, v106, v107
	v_cvt_pk_bf16_f32 v4, v108, v109
	v_cvt_pk_bf16_f32 v5, v110, v111
	s_waitcnt lgkmcnt(6)
	s_nop 0
	v_mfma_f32_32x32x16_bf16 v[64:79], v[6:9], v[2:5], v[64:79]
	s_waitcnt lgkmcnt(4)
	v_mfma_f32_32x32x16_bf16 v[48:63], v[10:13], v[2:5], v[48:63]
	s_waitcnt lgkmcnt(2)
	v_mfma_f32_32x32x16_bf16 v[32:47], v[100:103], v[2:5], v[32:47]
	ds_read_b64_tr_b16 v[6:7], v14 offset:57344
	ds_read_b64_tr_b16 v[8:9], v15 offset:57344
	ds_read_b64_tr_b16 v[10:11], v202 offset:57344
	ds_read_b64_tr_b16 v[12:13], v203 offset:57344
	ds_read_b64_tr_b16 v[96:97], v204 offset:57344
	ds_read_b64_tr_b16 v[98:99], v205 offset:57344
	ds_read_b64_tr_b16 v[100:101], v206 offset:57344
	ds_read_b64_tr_b16 v[102:103], v207 offset:57344
	s_waitcnt lgkmcnt(8)
	v_mfma_f32_32x32x16_bf16 v[16:31], v[112:115], v[2:5], v[16:31]
	v_add_f32_e32 v0, v104, v0
	v_add_f32_e32 v0, v105, v0
	v_add_f32_e32 v0, v106, v0
	v_add_f32_e32 v0, v107, v0
	v_add_f32_e32 v0, v108, v0
	v_add_f32_e32 v0, v109, v0
	v_add_f32_e32 v0, v110, v0
	v_add_f32_e32 v0, v111, v0
	v_exp_f32_e32 v112, v80
	v_exp_f32_e32 v113, v81
	v_exp_f32_e32 v114, v82
	v_exp_f32_e32 v115, v83
	v_exp_f32_e32 v124, v84
	v_exp_f32_e32 v125, v85
	v_exp_f32_e32 v126, v86
	v_exp_f32_e32 v127, v87
	v_cvt_pk_bf16_f32 v2, v112, v113
	v_cvt_pk_bf16_f32 v3, v114, v115
	v_cvt_pk_bf16_f32 v4, v124, v125
	v_cvt_pk_bf16_f32 v5, v126, v127
	s_waitcnt lgkmcnt(6)
	s_nop 0
	v_mfma_f32_32x32x16_bf16 v[64:79], v[6:9], v[2:5], v[64:79]
	s_waitcnt lgkmcnt(4)
	v_mfma_f32_32x32x16_bf16 v[48:63], v[10:13], v[2:5], v[48:63]
	ds_read_b64_tr_b16 v[6:7], v14 offset:61440
	ds_read_b64_tr_b16 v[8:9], v15 offset:61440
	ds_read_b64_tr_b16 v[10:11], v202 offset:61440
	ds_read_b64_tr_b16 v[12:13], v203 offset:61440
	ds_read_b64_tr_b16 v[80:81], v204 offset:61440
	ds_read_b64_tr_b16 v[82:83], v205 offset:61440
	ds_read_b64_tr_b16 v[84:85], v206 offset:61440
	ds_read_b64_tr_b16 v[86:87], v207 offset:61440
	s_waitcnt lgkmcnt(10)
	v_mfma_f32_32x32x16_bf16 v[32:47], v[96:99], v[2:5], v[32:47]
	s_waitcnt lgkmcnt(8)
	v_mfma_f32_32x32x16_bf16 v[16:31], v[100:103], v[2:5], v[16:31]
	v_add_f32_e32 v0, v112, v0
	v_add_f32_e32 v0, v113, v0
	v_add_f32_e32 v0, v114, v0
	v_add_f32_e32 v0, v115, v0
	v_add_f32_e32 v0, v124, v0
	v_add_f32_e32 v0, v125, v0
	v_add_f32_e32 v0, v126, v0
	v_add_f32_e32 v0, v127, v0
	v_exp_f32_e32 v14, v88
	v_exp_f32_e32 v15, v89
	v_exp_f32_e32 v88, v90
	v_exp_f32_e32 v89, v91
	v_exp_f32_e32 v90, v92
	v_exp_f32_e32 v91, v93
	v_exp_f32_e32 v92, v94
	v_exp_f32_e32 v93, v95
	v_cvt_pk_bf16_f32 v2, v14, v15
	v_cvt_pk_bf16_f32 v3, v88, v89
	v_cvt_pk_bf16_f32 v4, v90, v91
	v_cvt_pk_bf16_f32 v5, v92, v93
	s_waitcnt lgkmcnt(6)
	s_nop 0
	v_mfma_f32_32x32x16_bf16 v[64:79], v[6:9], v[2:5], v[64:79]
	s_waitcnt lgkmcnt(4)
	v_mfma_f32_32x32x16_bf16 v[48:63], v[10:13], v[2:5], v[48:63]
	s_waitcnt lgkmcnt(2)
	v_mfma_f32_32x32x16_bf16 v[32:47], v[80:83], v[2:5], v[32:47]
	s_waitcnt lgkmcnt(0)
	v_mfma_f32_32x32x16_bf16 v[16:31], v[84:87], v[2:5], v[16:31]
	v_add_f32_e32 v0, v14, v0
	v_add_f32_e32 v0, v15, v0
	v_add_f32_e32 v0, v88, v0
	v_add_f32_e32 v0, v89, v0
	v_add_f32_e32 v0, v90, v0
	v_add_f32_e32 v0, v91, v0
	v_add_f32_e32 v0, v92, v0
	v_add_f32_e32 v0, v93, v0
	s_andn2_b64 vcc, exec, s[12:13]
	v_mov_b32_e32 v201, v0
	s_cbranch_vccnz .LBB0_331
	s_cmp_eq_u32 s82, 2
	s_cselect_b32 s12, s51, s22
	s_lshl_b32 s12, s12, 7
	s_lshl_b32 s13, s51, 7
	s_sub_i32 s12, s12, s24
	v_log_f32_e32 v0, v201
	s_addk_i32 s12, 0x80
	s_sub_i32 s13, s50, s13
	v_cvt_f32_i32_e32 v3, s13
	v_cvt_f32_i32_e32 v2, s12
	v_add_f32_e32 v0, v180, v0
	s_mov_b32 s12, 0xc21044fe
	v_sub_f32_e32 v0, v197, v0
	v_pk_fma_f32 v[2:3], v[176:177], v[2:3], s[12:13] op_sel_hi:[1,1,0]
	s_nop 0
	v_cmp_gt_f32_e64 s[40:41], v0, v3
	v_cmp_gt_f32_e32 vcc, v0, v2
	s_and_saveexec_b64 s[12:13], s[38:39]
	s_cbranch_execz .LBB0_330
	s_and_b32 s14, s83, 8
	s_lshl_b32 s14, s14, 2
	s_add_i32 s16, s48, s14
	s_cmp_lg_u64 s[40:41], 0
	s_cselect_b64 s[14:15], -1, 0
	s_cmp_eq_u64 vcc, 0
	v_cndmask_b32_e64 v0, 0, 1, s[14:15]
	s_cselect_b32 s14, 0, 2
	v_or_b32_e32 v0, s14, v0
	v_mov_b32_e32 v2, s16
	ds_write_b32 v2, v0

.LBB0_340:
	v_readlane_b32 s82, v255, 52
	v_readlane_b32 s83, v255, 53
	s_cbranch_execz .LBB0_292
	s_mov_b64 s[8:9], 0
	s_nop 0
